# v23 + P1 K-loop head: per-iteration vmcnt(0) drain removed (the rebalanced vmcnt(8)/(6) protocol already covers every stage buffer)
# baseline (speedup 1.0000x reference)
; #define PG8_STAGE(bufoff, gbase, voff) do { _Pragma("unroll") for (int _i = 0; _i < 2; ++_i) { \
;         const unsigned m0v_ = (unsigned)(uintptr_t)(lds + (bufoff) + ldsw + _i * 8192); \
;         asm volatile("s_mov_b32 m0, %0\n\ts_nop 0\n\tglobal_load_lds_dwordx4 %1, %2\n\ts_nop 1" :: "s"(m0v_), "v"((voff)[_i]), "s"((const char*)(gbase)) : "m0", "memory"); } } while (0)
; #define PG8_LDA(dst, b, h) do { _Pragma("unroll") for (int m = 0; m < 4; ++m) _Pragma("unroll") for (int k = 0; k < 2; ++k) dst[m][k] = *(const LAS bf16x8*)(lds + PG8_SA(b, h) + aoff + m * 2048 + k * 1024); } while (0)
; #define PG8_LDB(dst, b, h) do { _Pragma("unroll") for (int n = 0; n < 2; ++n) _Pragma("unroll") for (int k = 0; k < 2; ++k) dst[n][k] = *(const LAS bf16x8*)(lds + PG8_SB(b, h) + boff + n * 2048 + k * 1024); } while (0)
; #define PG8_MMA(ai, bj, At, Bt) do { _Pragma("unroll") for (int m = 0; m < 4; ++m) _Pragma("unroll") for (int n = 0; n < 2; ++n) _Pragma("unroll") for (int k = 0; k < 2; ++k) \
;         acc[ai][bj][m][n] = __builtin_amdgcn_mfma_f32_16x16x32_bf16(Bt[n][k], At[m][k], acc[ai][bj][m][n], 0, 0, 0); } while (0)
; template <class Prob, class Epi, class Sched>
; __device__ __forceinline__ void gemm_phase(LAS unsigned char* lds, const Prob& P, const Sched& S, const Epi& E) {
;     ...
;         for (int t = 0; t < nt; t += 2) {
;             const bool last = (t == nt - 2);
;             if (Epi::MID_T >= 0) { if (t == Epi::MID_T) E.mid(acc, cur, slot, wr, wc, fr, fq, lds); }
;             const char* a1 = cA + (size_t)(t + 1) * kstep;
;             const char* a2 = last ? nA : cA + (size_t)(t + 2) * kstep; const char* b2 = last ? nB : cB + (size_t)(t + 2) * kstep;
;             const char* a3 = a2 + kstep; const char* b3 = b2 + kstep;
;             PG8_LDB(B0, 0, 0); PG8_LDB(B1, 0, 1); PG8_SCHED; PG8_LDA(At, 0, 0); PG8_STAGE(PG8_SA(1, 1), a1 + hstepA, voffA);
;             PG8_WAIT_V(8); PG8_WAIT_L(0); PG8_BAR; __builtin_amdgcn_s_setprio(1); PG8_MMA(0, 0, At, B0); PG8_MMA(0, 1, At, B1); __builtin_amdgcn_s_setprio(0); PG8_BAR; PG8_SCHED;
;             PG8_LDA(At, 0, 1); PG8_STAGE(PG8_SB(0, 0), b2, voffB); PG8_STAGE(PG8_SB(0, 1), b2 + hstepB, voffB); PG8_STAGE(PG8_SA(0, 0), a2, voffA);
;             PG8_WAIT_V(8); PG8_WAIT_L(0); PG8_BAR; __builtin_amdgcn_s_setprio(1); PG8_MMA(1, 0, At, B0); PG8_MMA(1, 1, At, B1); __builtin_amdgcn_s_setprio(0); PG8_BAR; PG8_SCHED;
.LBB0_270:
	ds_read_b128 v[136:139], v163
	ds_read_b128 v[140:143], v163 offset:1024
	ds_read_b128 v[144:147], v163 offset:2048
	ds_read_b128 v[148:151], v163 offset:3072
	ds_read_b128 v[152:155], v164
	ds_read_b128 v[156:159], v164 offset:1024
	ds_read_b128 v[170:173], v164 offset:2048
	ds_read_b128 v[174:177], v164 offset:3072
	ds_read_b128 v[178:181], v165
	ds_read_b128 v[182:185], v165 offset:1024
	ds_read_b128 v[186:189], v165 offset:2048
	ds_read_b128 v[190:193], v165 offset:3072
	ds_read_b128 v[194:197], v165 offset:4096
	ds_read_b128 v[198:201], v165 offset:5120
	ds_read_b128 v[202:205], v165 offset:6144
	ds_read_b128 v[206:209], v165 offset:7168
	s_sub_u32 s98, s4, 0x80000
	s_subb_u32 s99, s5, 0
	s_mov_b32 m0, s72
	s_nop 0
	global_load_lds_dwordx4 v1, s[98:99]
	s_nop 1
	s_nop 0
	s_mov_b32 m0, s73
	s_nop 0
	global_load_lds_dwordx4 v161, s[98:99]
	s_nop 1
	s_mov_b32 m0, s76
	s_nop 0
	global_load_lds_dwordx4 v1, s[4:5]
	s_nop 1
	s_nop 0
	s_mov_b32 m0, s77
	s_nop 0
	global_load_lds_dwordx4 v161, s[4:5]
	s_nop 1
	s_waitcnt vmcnt(8)
	s_waitcnt lgkmcnt(0)
	s_setprio 1
	s_barrier
	v_mfma_f32_16x16x32_bf16 v[126:129], v[136:139], v[178:181], v[126:129]
	v_mfma_f32_16x16x32_bf16 v[122:125], v[144:147], v[178:181], v[122:125]
	s_cmp_eq_u32 s71, 28
	v_mfma_f32_16x16x32_bf16 v[110:113], v[136:139], v[186:189], v[110:113]
	s_cselect_b32 s68, s46, s15
	v_mfma_f32_16x16x32_bf16 v[106:109], v[144:147], v[186:189], v[106:109]
	s_cselect_b32 s69, s47, s43
	v_mfma_f32_16x16x32_bf16 v[94:97], v[136:139], v[194:197], v[94:97]
	s_cselect_b32 s54, s48, s45
	v_mfma_f32_16x16x32_bf16 v[90:93], v[144:147], v[194:197], v[90:93]
	s_cselect_b32 s55, s49, s70
	v_mfma_f32_16x16x32_bf16 v[78:81], v[136:139], v[202:205], v[78:81]
	s_add_u32 s6, s68, 0x80
	v_mfma_f32_16x16x32_bf16 v[74:77], v[144:147], v[202:205], v[74:77]
	s_addc_u32 s7, s69, 0
	v_mfma_f32_16x16x32_bf16 v[118:121], v[152:155], v[178:181], v[118:121]
	v_mfma_f32_16x16x32_bf16 v[114:117], v[170:173], v[178:181], v[114:117]
	v_mfma_f32_16x16x32_bf16 v[102:105], v[152:155], v[186:189], v[102:105]
	v_mfma_f32_16x16x32_bf16 v[98:101], v[170:173], v[186:189], v[98:101]
	v_mfma_f32_16x16x32_bf16 v[86:89], v[152:155], v[194:197], v[86:89]
	v_mfma_f32_16x16x32_bf16 v[82:85], v[170:173], v[194:197], v[82:85]
	v_mfma_f32_16x16x32_bf16 v[70:73], v[152:155], v[202:205], v[70:73]
	v_mfma_f32_16x16x32_bf16 v[66:69], v[170:173], v[202:205], v[66:69]
	v_mfma_f32_16x16x32_bf16 v[126:129], v[140:143], v[182:185], v[126:129]
	v_mfma_f32_16x16x32_bf16 v[122:125], v[148:151], v[182:185], v[122:125]
	v_mfma_f32_16x16x32_bf16 v[110:113], v[140:143], v[190:193], v[110:113]
	v_mfma_f32_16x16x32_bf16 v[106:109], v[148:151], v[190:193], v[106:109]
	v_mfma_f32_16x16x32_bf16 v[94:97], v[140:143], v[198:201], v[94:97]
	v_mfma_f32_16x16x32_bf16 v[90:93], v[148:151], v[198:201], v[90:93]
	v_mfma_f32_16x16x32_bf16 v[78:81], v[140:143], v[206:209], v[78:81]
	v_mfma_f32_16x16x32_bf16 v[74:77], v[148:151], v[206:209], v[74:77]
	v_mfma_f32_16x16x32_bf16 v[118:121], v[156:159], v[182:185], v[118:121]
	v_mfma_f32_16x16x32_bf16 v[114:117], v[174:177], v[182:185], v[114:117]
	v_mfma_f32_16x16x32_bf16 v[102:105], v[156:159], v[190:193], v[102:105]
	v_mfma_f32_16x16x32_bf16 v[98:101], v[174:177], v[190:193], v[98:101]
	v_mfma_f32_16x16x32_bf16 v[86:89], v[156:159], v[198:201], v[86:89]
	v_mfma_f32_16x16x32_bf16 v[82:85], v[174:177], v[198:201], v[82:85]
	v_mfma_f32_16x16x32_bf16 v[70:73], v[156:159], v[206:209], v[70:73]
	v_mfma_f32_16x16x32_bf16 v[66:69], v[174:177], v[206:209], v[66:69]
	s_barrier
	s_setprio 0
	ds_read_b128 v[178:181], v165 offset:16384
	ds_read_b128 v[182:185], v165 offset:17408
	ds_read_b128 v[186:189], v165 offset:18432
	ds_read_b128 v[190:193], v165 offset:19456
	ds_read_b128 v[194:197], v165 offset:20480
	ds_read_b128 v[198:201], v165 offset:21504
	ds_read_b128 v[202:205], v165 offset:22528
	ds_read_b128 v[206:209], v165 offset:23552
	s_mov_b32 m0, s34
	s_nop 0
	global_load_lds_dwordx4 v160, s[54:55]
	s_nop 1
	s_add_u32 s82, s54, 0x80000
	s_mov_b32 m0, s35
	s_nop 0
	global_load_lds_dwordx4 v162, s[54:55]
	s_nop 1
	s_addc_u32 s83, s55, 0
	s_mov_b32 m0, s53
	s_nop 0
	global_load_lds_dwordx4 v160, s[82:83]
	s_nop 1
	s_nop 0
	s_mov_b32 m0, s56
	s_nop 0
	global_load_lds_dwordx4 v162, s[82:83]
	s_nop 1
	s_nop 0
	s_waitcnt vmcnt(6)
	s_waitcnt lgkmcnt(0)
	s_setprio 1
	s_barrier
	v_mfma_f32_16x16x32_bf16 v[62:65], v[136:139], v[178:181], v[62:65]
	v_mfma_f32_16x16x32_bf16 v[58:61], v[144:147], v[178:181], v[58:61]
	v_mfma_f32_16x16x32_bf16 v[46:49], v[136:139], v[186:189], v[46:49]
	v_mfma_f32_16x16x32_bf16 v[42:45], v[144:147], v[186:189], v[42:45]
	v_mfma_f32_16x16x32_bf16 v[30:33], v[136:139], v[194:197], v[30:33]
	v_mfma_f32_16x16x32_bf16 v[26:29], v[144:147], v[194:197], v[26:29]
	v_mfma_f32_16x16x32_bf16 v[14:17], v[136:139], v[202:205], v[14:17]
	v_mfma_f32_16x16x32_bf16 v[10:13], v[144:147], v[202:205], v[10:13]
	v_mfma_f32_16x16x32_bf16 v[54:57], v[152:155], v[178:181], v[54:57]
	v_mfma_f32_16x16x32_bf16 v[50:53], v[170:173], v[178:181], v[50:53]
	v_mfma_f32_16x16x32_bf16 v[38:41], v[152:155], v[186:189], v[38:41]
	v_mfma_f32_16x16x32_bf16 v[34:37], v[170:173], v[186:189], v[34:37]
	v_mfma_f32_16x16x32_bf16 v[22:25], v[152:155], v[194:197], v[22:25]
	v_mfma_f32_16x16x32_bf16 v[18:21], v[170:173], v[194:197], v[18:21]
	v_mfma_f32_16x16x32_bf16 v[6:9], v[152:155], v[202:205], v[6:9]
	v_mfma_f32_16x16x32_bf16 v[2:5], v[170:173], v[202:205], v[2:5]
	v_mfma_f32_16x16x32_bf16 v[62:65], v[140:143], v[182:185], v[62:65]
	v_mfma_f32_16x16x32_bf16 v[58:61], v[148:151], v[182:185], v[58:61]
	v_mfma_f32_16x16x32_bf16 v[46:49], v[140:143], v[190:193], v[46:49]
	v_mfma_f32_16x16x32_bf16 v[42:45], v[148:151], v[190:193], v[42:45]
	v_mfma_f32_16x16x32_bf16 v[30:33], v[140:143], v[198:201], v[30:33]
	v_mfma_f32_16x16x32_bf16 v[26:29], v[148:151], v[198:201], v[26:29]
	v_mfma_f32_16x16x32_bf16 v[14:17], v[140:143], v[206:209], v[14:17]
	v_mfma_f32_16x16x32_bf16 v[10:13], v[148:151], v[206:209], v[10:13]
	v_mfma_f32_16x16x32_bf16 v[54:57], v[156:159], v[182:185], v[54:57]
	v_mfma_f32_16x16x32_bf16 v[50:53], v[174:177], v[182:185], v[50:53]
	v_mfma_f32_16x16x32_bf16 v[38:41], v[156:159], v[190:193], v[38:41]
	v_mfma_f32_16x16x32_bf16 v[34:37], v[174:177], v[190:193], v[34:37]
	v_mfma_f32_16x16x32_bf16 v[22:25], v[156:159], v[198:201], v[22:25]
	v_mfma_f32_16x16x32_bf16 v[18:21], v[174:177], v[198:201], v[18:21]
	v_mfma_f32_16x16x32_bf16 v[6:9], v[156:159], v[206:209], v[6:9]
	v_mfma_f32_16x16x32_bf16 v[2:5], v[174:177], v[206:209], v[2:5]
	s_barrier
; #define PG8_STAGE(bufoff, gbase, voff) do { _Pragma("unroll") for (int _i = 0; _i < 2; ++_i) { \
;         const unsigned m0v_ = (unsigned)(uintptr_t)(lds + (bufoff) + ldsw + _i * 8192); \
;         asm volatile("s_mov_b32 m0, %0\n\ts_nop 0\n\tglobal_load_lds_dwordx4 %1, %2\n\ts_nop 1" :: "s"(m0v_), "v"((voff)[_i]), "s"((const char*)(gbase)) : "m0", "memory"); } } while (0)
; #define PG8_LDA(dst, b, h) do { _Pragma("unroll") for (int m = 0; m < 4; ++m) _Pragma("unroll") for (int k = 0; k < 2; ++k) dst[m][k] = *(const LAS bf16x8*)(lds + PG8_SA(b, h) + aoff + m * 2048 + k * 1024); } while (0)
; #define PG8_LDB(dst, b, h) do { _Pragma("unroll") for (int n = 0; n < 2; ++n) _Pragma("unroll") for (int k = 0; k < 2; ++k) dst[n][k] = *(const LAS bf16x8*)(lds + PG8_SB(b, h) + boff + n * 2048 + k * 1024); } while (0)
; #define PG8_MMA(ai, bj, At, Bt) do { _Pragma("unroll") for (int m = 0; m < 4; ++m) _Pragma("unroll") for (int n = 0; n < 2; ++n) _Pragma("unroll") for (int k = 0; k < 2; ++k) \
;         acc[ai][bj][m][n] = __builtin_amdgcn_mfma_f32_16x16x32_bf16(Bt[n][k], At[m][k], acc[ai][bj][m][n], 0, 0, 0); } while (0)
; #define PG8_WAIT_V(n) asm volatile("s_waitcnt vmcnt(" #n ")" ::: "memory")
; #define PG8_WAIT_L(n) asm volatile("s_waitcnt lgkmcnt(" #n ")" ::: "memory")
; #define PG8_BAR __builtin_amdgcn_s_barrier()
; #define PG8_SCHED __builtin_amdgcn_sched_barrier(0)
; template <class Prob, class Epi, class Sched>
; __device__ __forceinline__ void gemm_phase(LAS unsigned char* lds, const Prob& P, const Sched& S, const Epi& E) {
;     ...
;             PG8_LDB(B0, 1, 0); PG8_LDB(B1, 1, 1); PG8_SCHED; PG8_LDA(At, 1, 0); PG8_STAGE(PG8_SA(0, 1), a2 + hstepA, voffA);
;             PG8_WAIT_V(8); PG8_WAIT_L(0); PG8_BAR; __builtin_amdgcn_s_setprio(1); PG8_MMA(0, 0, At, B0); PG8_MMA(0, 1, At, B1); __builtin_amdgcn_s_setprio(0); PG8_BAR; PG8_SCHED;
;             PG8_LDA(At, 1, 1); PG8_STAGE(PG8_SB(1, 0), b3, voffB); PG8_STAGE(PG8_SB(1, 1), b3 + hstepB, voffB); PG8_STAGE(PG8_SA(1, 0), a3, voffA);
;             PG8_WAIT_V(8); PG8_WAIT_L(0); PG8_BAR; __builtin_amdgcn_s_setprio(1); PG8_MMA(1, 0, At, B0); PG8_MMA(1, 1, At, B1); __builtin_amdgcn_s_setprio(0); PG8_BAR; PG8_SCHED;
;         }
;         if (wr == 0) PG8_BAR;
	s_setprio 0
	ds_read_b128 v[136:139], v166
	ds_read_b128 v[140:143], v166 offset:1024
	ds_read_b128 v[144:147], v166 offset:2048
	ds_read_b128 v[148:151], v166 offset:3072
	ds_read_b128 v[152:155], v167
	ds_read_b128 v[156:159], v167 offset:1024
	ds_read_b128 v[170:173], v167 offset:2048
	ds_read_b128 v[174:177], v167 offset:3072
	ds_read_b128 v[178:181], v165 offset:32768
	ds_read_b128 v[182:185], v165 offset:33792
	ds_read_b128 v[186:189], v165 offset:34816
	ds_read_b128 v[190:193], v165 offset:35840
	ds_read_b128 v[194:197], v165 offset:36864
	ds_read_b128 v[198:201], v165 offset:37888
	ds_read_b128 v[202:205], v165 offset:38912
	ds_read_b128 v[206:209], v165 offset:39936
	s_mov_b32 m0, s3
	s_nop 0
	global_load_lds_dwordx4 v1, s[68:69]
	s_nop 1
	s_nop 0
	s_mov_b32 m0, s57
	s_nop 0
	global_load_lds_dwordx4 v161, s[68:69]
	s_nop 1
	s_add_u32 s68, s68, 0x80000
	s_addc_u32 s69, s69, 0
	s_mov_b32 m0, s58
	s_nop 0
	global_load_lds_dwordx4 v1, s[68:69]
	s_nop 1
	s_nop 0
	s_mov_b32 m0, s59
	s_nop 0
	global_load_lds_dwordx4 v161, s[68:69]
	s_nop 1
	s_waitcnt vmcnt(8)
	s_waitcnt lgkmcnt(0)
	s_setprio 1
	s_barrier
	v_mfma_f32_16x16x32_bf16 v[126:129], v[136:139], v[178:181], v[126:129]
	v_mfma_f32_16x16x32_bf16 v[122:125], v[144:147], v[178:181], v[122:125]
	v_mfma_f32_16x16x32_bf16 v[110:113], v[136:139], v[186:189], v[110:113]
	v_mfma_f32_16x16x32_bf16 v[106:109], v[144:147], v[186:189], v[106:109]
	v_mfma_f32_16x16x32_bf16 v[94:97], v[136:139], v[194:197], v[94:97]
	v_mfma_f32_16x16x32_bf16 v[90:93], v[144:147], v[194:197], v[90:93]
	v_mfma_f32_16x16x32_bf16 v[78:81], v[136:139], v[202:205], v[78:81]
	v_mfma_f32_16x16x32_bf16 v[74:77], v[144:147], v[202:205], v[74:77]
	v_mfma_f32_16x16x32_bf16 v[118:121], v[152:155], v[178:181], v[118:121]
	v_mfma_f32_16x16x32_bf16 v[114:117], v[170:173], v[178:181], v[114:117]
	v_mfma_f32_16x16x32_bf16 v[102:105], v[152:155], v[186:189], v[102:105]
	v_mfma_f32_16x16x32_bf16 v[98:101], v[170:173], v[186:189], v[98:101]
	v_mfma_f32_16x16x32_bf16 v[86:89], v[152:155], v[194:197], v[86:89]
	v_mfma_f32_16x16x32_bf16 v[82:85], v[170:173], v[194:197], v[82:85]
	v_mfma_f32_16x16x32_bf16 v[70:73], v[152:155], v[202:205], v[70:73]
	v_mfma_f32_16x16x32_bf16 v[66:69], v[170:173], v[202:205], v[66:69]
	v_mfma_f32_16x16x32_bf16 v[126:129], v[140:143], v[182:185], v[126:129]
	v_mfma_f32_16x16x32_bf16 v[122:125], v[148:151], v[182:185], v[122:125]
	v_mfma_f32_16x16x32_bf16 v[110:113], v[140:143], v[190:193], v[110:113]
	v_mfma_f32_16x16x32_bf16 v[106:109], v[148:151], v[190:193], v[106:109]
	v_mfma_f32_16x16x32_bf16 v[94:97], v[140:143], v[198:201], v[94:97]
	v_mfma_f32_16x16x32_bf16 v[90:93], v[148:151], v[198:201], v[90:93]
	v_mfma_f32_16x16x32_bf16 v[78:81], v[140:143], v[206:209], v[78:81]
	v_mfma_f32_16x16x32_bf16 v[74:77], v[148:151], v[206:209], v[74:77]
	v_mfma_f32_16x16x32_bf16 v[118:121], v[156:159], v[182:185], v[118:121]
	v_mfma_f32_16x16x32_bf16 v[114:117], v[174:177], v[182:185], v[114:117]
	v_mfma_f32_16x16x32_bf16 v[102:105], v[156:159], v[190:193], v[102:105]
	v_mfma_f32_16x16x32_bf16 v[98:101], v[174:177], v[190:193], v[98:101]
	v_mfma_f32_16x16x32_bf16 v[86:89], v[156:159], v[198:201], v[86:89]
	v_mfma_f32_16x16x32_bf16 v[82:85], v[174:177], v[198:201], v[82:85]
	v_mfma_f32_16x16x32_bf16 v[70:73], v[156:159], v[206:209], v[70:73]
	v_mfma_f32_16x16x32_bf16 v[66:69], v[174:177], v[206:209], v[66:69]
	s_barrier
	s_setprio 0
	ds_read_b128 v[178:181], v165 offset:49152
	ds_read_b128 v[182:185], v165 offset:50176
	ds_read_b128 v[186:189], v165 offset:51200
	ds_read_b128 v[190:193], v165 offset:52224
	ds_read_b128 v[194:197], v165 offset:53248
	ds_read_b128 v[198:201], v165 offset:54272
	ds_read_b128 v[202:205], v165 offset:55296
	ds_read_b128 v[206:209], v165 offset:56320
	s_add_u32 s68, s54, 0x80
	s_addc_u32 s69, s55, 0
	s_mov_b32 m0, s64
	s_nop 0
	global_load_lds_dwordx4 v160, s[68:69]
	s_nop 1
	s_add_u32 s54, s54, 0x80080
	s_mov_b32 m0, s65
	s_nop 0
	global_load_lds_dwordx4 v162, s[68:69]
	s_nop 1
	s_addc_u32 s55, s55, 0
	s_mov_b32 m0, s74
	s_nop 0
	global_load_lds_dwordx4 v160, s[54:55]
	s_nop 1
	s_nop 0
	s_mov_b32 m0, s75
	s_nop 0
	global_load_lds_dwordx4 v162, s[54:55]
	s_nop 1
	s_nop 0
	s_waitcnt vmcnt(6)
	s_waitcnt lgkmcnt(0)
	s_setprio 1
	s_barrier
	v_mfma_f32_16x16x32_bf16 v[62:65], v[136:139], v[178:181], v[62:65]
	v_mfma_f32_16x16x32_bf16 v[58:61], v[144:147], v[178:181], v[58:61]
	s_add_i32 s71, s71, 2
	v_mfma_f32_16x16x32_bf16 v[46:49], v[136:139], v[186:189], v[46:49]
	s_add_u32 s15, s15, 0x100
	v_mfma_f32_16x16x32_bf16 v[42:45], v[144:147], v[186:189], v[42:45]
	s_addc_u32 s43, s43, 0
	v_mfma_f32_16x16x32_bf16 v[30:33], v[136:139], v[194:197], v[30:33]
	s_add_u32 s45, s45, 0x100
	v_mfma_f32_16x16x32_bf16 v[26:29], v[144:147], v[194:197], v[26:29]
	s_addc_u32 s70, s70, 0
	v_mfma_f32_16x16x32_bf16 v[14:17], v[136:139], v[202:205], v[14:17]
	s_add_u32 s4, s4, 0x100
	v_mfma_f32_16x16x32_bf16 v[10:13], v[144:147], v[202:205], v[10:13]
	s_addc_u32 s5, s5, 0
	v_mfma_f32_16x16x32_bf16 v[54:57], v[152:155], v[178:181], v[54:57]
	v_mfma_f32_16x16x32_bf16 v[50:53], v[170:173], v[178:181], v[50:53]
	v_mfma_f32_16x16x32_bf16 v[38:41], v[152:155], v[186:189], v[38:41]
	v_mfma_f32_16x16x32_bf16 v[34:37], v[170:173], v[186:189], v[34:37]
	v_mfma_f32_16x16x32_bf16 v[22:25], v[152:155], v[194:197], v[22:25]
	v_mfma_f32_16x16x32_bf16 v[18:21], v[170:173], v[194:197], v[18:21]
	v_mfma_f32_16x16x32_bf16 v[6:9], v[152:155], v[202:205], v[6:9]
	v_mfma_f32_16x16x32_bf16 v[2:5], v[170:173], v[202:205], v[2:5]
	v_mfma_f32_16x16x32_bf16 v[62:65], v[140:143], v[182:185], v[62:65]
	v_mfma_f32_16x16x32_bf16 v[58:61], v[148:151], v[182:185], v[58:61]
	v_mfma_f32_16x16x32_bf16 v[46:49], v[140:143], v[190:193], v[46:49]
	v_mfma_f32_16x16x32_bf16 v[42:45], v[148:151], v[190:193], v[42:45]
	v_mfma_f32_16x16x32_bf16 v[30:33], v[140:143], v[198:201], v[30:33]
	v_mfma_f32_16x16x32_bf16 v[26:29], v[148:151], v[198:201], v[26:29]
	v_mfma_f32_16x16x32_bf16 v[14:17], v[140:143], v[206:209], v[14:17]
	v_mfma_f32_16x16x32_bf16 v[10:13], v[148:151], v[206:209], v[10:13]
	v_mfma_f32_16x16x32_bf16 v[54:57], v[156:159], v[182:185], v[54:57]
	v_mfma_f32_16x16x32_bf16 v[50:53], v[174:177], v[182:185], v[50:53]
	v_mfma_f32_16x16x32_bf16 v[38:41], v[156:159], v[190:193], v[38:41]
	v_mfma_f32_16x16x32_bf16 v[34:37], v[174:177], v[190:193], v[34:37]
	v_mfma_f32_16x16x32_bf16 v[22:25], v[156:159], v[198:201], v[22:25]
	v_mfma_f32_16x16x32_bf16 v[18:21], v[174:177], v[198:201], v[18:21]
	v_mfma_f32_16x16x32_bf16 v[6:9], v[156:159], v[206:209], v[6:9]
	v_mfma_f32_16x16x32_bf16 v[2:5], v[174:177], v[206:209], v[2:5]
	s_barrier
	s_setprio 0
	s_cmp_gt_u32 s71, 29
	s_cbranch_scc0 .LBB0_270
	s_and_b64 vcc, exec, s[40:41]
	s_cbranch_vccz .LBB0_273
	s_barrier
